# write-through (sc1) stores for the G4 (up projection) output tile, so the grid barrier's L2 write-back has nothing to flush
# speedup vs baseline: 1.0081x; 1.0081x over previous
.LBB0_1243:
	v_lshl_add_u32 v142, s8, 8, v146
	v_and_b32_e32 v140, -16, v142
	v_lshlrev_b32_e32 v140, 6, v140
	v_lshl_add_u32 v140, v186, 4, v140
	v_add_u32_e32 v230, 0x2000, v140
	global_load_dwordx4 v[198:201], v140, s[2:3]
	global_load_dwordx4 v[202:205], v140, s[2:3] offset:1024
	global_load_dwordx4 v[206:209], v140, s[2:3] offset:2048
	global_load_dwordx4 v[210:213], v140, s[2:3] offset:3072
	global_load_dwordx4 v[214:217], v230, s[2:3]
	global_load_dwordx4 v[218:221], v230, s[2:3] offset:1024
	global_load_dwordx4 v[222:225], v230, s[2:3] offset:2048
	global_load_dwordx4 v[226:229], v230, s[2:3] offset:3072
	v_and_b32_e32 v231, 15, v186
	v_lshlrev_b32_e32 v231, 4, v231
	s_waitcnt vmcnt(0)
	v_add_f32_e32 v198, v198, v199
	v_add_f32_e32 v200, v200, v201
	v_add_f32_e32 v202, v202, v203
	v_add_f32_e32 v204, v204, v205
	v_add_f32_e32 v206, v206, v207
	v_add_f32_e32 v208, v208, v209
	v_add_f32_e32 v210, v210, v211
	v_add_f32_e32 v212, v212, v213
	v_add_f32_e32 v214, v214, v215
	v_add_f32_e32 v216, v216, v217
	v_add_f32_e32 v218, v218, v219
	v_add_f32_e32 v220, v220, v221
	v_add_f32_e32 v222, v222, v223
	v_add_f32_e32 v224, v224, v225
	v_add_f32_e32 v226, v226, v227
	v_add_f32_e32 v228, v228, v229
	v_add_f32_e32 v198, v198, v200
	v_add_f32_e32 v202, v202, v204
	v_add_f32_e32 v206, v206, v208
	v_add_f32_e32 v210, v210, v212
	v_add_f32_e32 v214, v214, v216
	v_add_f32_e32 v218, v218, v220
	v_add_f32_e32 v222, v222, v224
	v_add_f32_e32 v226, v226, v228
	v_add_f32_dpp v198, v198, v198 quad_perm:[1,0,3,2] row_mask:0xf bank_mask:0xf
	v_add_f32_dpp v202, v202, v202 quad_perm:[1,0,3,2] row_mask:0xf bank_mask:0xf
	v_add_f32_dpp v206, v206, v206 quad_perm:[1,0,3,2] row_mask:0xf bank_mask:0xf
	v_add_f32_dpp v210, v210, v210 quad_perm:[1,0,3,2] row_mask:0xf bank_mask:0xf
	v_add_f32_dpp v214, v214, v214 quad_perm:[1,0,3,2] row_mask:0xf bank_mask:0xf
	v_add_f32_dpp v218, v218, v218 quad_perm:[1,0,3,2] row_mask:0xf bank_mask:0xf
	v_add_f32_dpp v222, v222, v222 quad_perm:[1,0,3,2] row_mask:0xf bank_mask:0xf
	v_add_f32_dpp v226, v226, v226 quad_perm:[1,0,3,2] row_mask:0xf bank_mask:0xf
	v_add_f32_dpp v198, v198, v198 quad_perm:[2,3,0,1] row_mask:0xf bank_mask:0xf
	v_add_f32_dpp v202, v202, v202 quad_perm:[2,3,0,1] row_mask:0xf bank_mask:0xf
	v_add_f32_dpp v206, v206, v206 quad_perm:[2,3,0,1] row_mask:0xf bank_mask:0xf
	v_add_f32_dpp v210, v210, v210 quad_perm:[2,3,0,1] row_mask:0xf bank_mask:0xf
	v_add_f32_dpp v214, v214, v214 quad_perm:[2,3,0,1] row_mask:0xf bank_mask:0xf
	v_add_f32_dpp v218, v218, v218 quad_perm:[2,3,0,1] row_mask:0xf bank_mask:0xf
	v_add_f32_dpp v222, v222, v222 quad_perm:[2,3,0,1] row_mask:0xf bank_mask:0xf
	v_add_f32_dpp v226, v226, v226 quad_perm:[2,3,0,1] row_mask:0xf bank_mask:0xf
	v_fmamk_f32 v198, v198, 0x3a800000, v182
	v_fmamk_f32 v202, v202, 0x3a800000, v182
	v_fmamk_f32 v206, v206, 0x3a800000, v182
	v_fmamk_f32 v210, v210, 0x3a800000, v182
	v_fmamk_f32 v214, v214, 0x3a800000, v182
	v_fmamk_f32 v218, v218, 0x3a800000, v182
	v_fmamk_f32 v222, v222, 0x3a800000, v182
	v_fmamk_f32 v226, v226, 0x3a800000, v182
	v_mul_f32_e32 v199, 0x4b800000, v198
	v_mul_f32_e32 v203, 0x4b800000, v202
	v_mul_f32_e32 v207, 0x4b800000, v206
	v_mul_f32_e32 v211, 0x4b800000, v210
	v_mul_f32_e32 v215, 0x4b800000, v214
	v_mul_f32_e32 v219, 0x4b800000, v218
	v_mul_f32_e32 v223, 0x4b800000, v222
	v_mul_f32_e32 v227, 0x4b800000, v226
	v_cmp_gt_f32_e32 vcc, 0x800000, v198
	s_nop 1
	v_cndmask_b32_e32 v200, v198, v199, vcc
	v_rsq_f32_e32 v200, v200
	s_nop 0
	v_mul_f32_e32 v201, 0x45800000, v200
	v_cndmask_b32_e32 v200, v200, v201, vcc
	v_cmp_gt_f32_e32 vcc, 0x800000, v202
	s_nop 1
	v_cndmask_b32_e32 v204, v202, v203, vcc
	v_rsq_f32_e32 v204, v204
	s_nop 0
	v_mul_f32_e32 v205, 0x45800000, v204
	v_cndmask_b32_e32 v204, v204, v205, vcc
	v_cmp_gt_f32_e32 vcc, 0x800000, v206
	s_nop 1
	v_cndmask_b32_e32 v208, v206, v207, vcc
	v_rsq_f32_e32 v208, v208
	s_nop 0
	v_mul_f32_e32 v209, 0x45800000, v208
	v_cndmask_b32_e32 v208, v208, v209, vcc
	v_cmp_gt_f32_e32 vcc, 0x800000, v210
	s_nop 1
	v_cndmask_b32_e32 v212, v210, v211, vcc
	v_rsq_f32_e32 v212, v212
	s_nop 0
	v_mul_f32_e32 v213, 0x45800000, v212
	v_cndmask_b32_e32 v212, v212, v213, vcc
	v_cmp_gt_f32_e32 vcc, 0x800000, v214
	s_nop 1
	v_cndmask_b32_e32 v216, v214, v215, vcc
	v_rsq_f32_e32 v216, v216
	s_nop 0
	v_mul_f32_e32 v217, 0x45800000, v216
	v_cndmask_b32_e32 v216, v216, v217, vcc
	v_cmp_gt_f32_e32 vcc, 0x800000, v218
	s_nop 1
	v_cndmask_b32_e32 v220, v218, v219, vcc
	v_rsq_f32_e32 v220, v220
	s_nop 0
	v_mul_f32_e32 v221, 0x45800000, v220
	v_cndmask_b32_e32 v220, v220, v221, vcc
	v_cmp_gt_f32_e32 vcc, 0x800000, v222
	s_nop 1
	v_cndmask_b32_e32 v224, v222, v223, vcc
	v_rsq_f32_e32 v224, v224
	s_nop 0
	v_mul_f32_e32 v225, 0x45800000, v224
	v_cndmask_b32_e32 v224, v224, v225, vcc
	v_cmp_gt_f32_e32 vcc, 0x800000, v226
	s_nop 1
	v_cndmask_b32_e32 v228, v226, v227, vcc
	v_rsq_f32_e32 v228, v228
	s_nop 0
	v_mul_f32_e32 v229, 0x45800000, v228
	v_cndmask_b32_e32 v228, v228, v229, vcc
	s_nop 1
	ds_bpermute_b32 v242, v231, v200
	ds_bpermute_b32 v243, v231, v204
	ds_bpermute_b32 v244, v231, v208
	ds_bpermute_b32 v245, v231, v212
	ds_bpermute_b32 v246, v231, v216
	ds_bpermute_b32 v247, v231, v220
	ds_bpermute_b32 v248, v231, v224
	ds_bpermute_b32 v249, v231, v228
	s_waitcnt lgkmcnt(0)
	v_ashrrev_i32_e32 v143, 31, v142
	v_lshlrev_b64 v[140:141], 6, v[142:143]
	v_lshl_add_u64 v[140:141], s[2:3], 0, v[140:141]
	v_lshl_or_b32 v140, s0, 8, v148
	s_movk_i32 s0, 0x1000
	v_mov_b32_e32 v144, v242
	v_mov_b32_e32 v145, v144
	v_cmp_gt_i32_e32 vcc, s0, v140
	s_and_saveexec_b64 s[0:1], vcc
	s_cbranch_execz .LBB0_1245
	v_mov_b32_e32 v150, v144
	v_mov_b32_e32 v151, v144
	v_mul_f32_e32 v126, v126, v144
	v_mul_f32_e32 v127, v127, v145
	v_mul_f32_e32 v122, v122, v144
	v_mul_f32_e32 v123, v123, v145
	v_mul_f32_e32 v128, v128, v150
	v_mul_f32_e32 v129, v129, v151
	v_max_f32_e32 v126, 0, v126
	v_max_f32_e32 v122, 0, v122
	v_max_f32_e32 v127, 0, v127
	v_max_f32_e32 v123, 0, v123
	v_mul_f32_e32 v124, v124, v150
	v_mul_f32_e32 v125, v125, v151
	v_mul_f32_e32 v126, v126, v126
	v_mul_f32_e32 v127, v127, v127
	v_mul_f32_e32 v150, v122, v122
	v_mul_f32_e32 v151, v123, v123
	v_max_f32_e32 v122, 0, v128
	v_max_f32_e32 v123, 0, v129
	v_max_f32_e32 v124, 0, v124
	v_max_f32_e32 v125, 0, v125
	v_mul_f32_e32 v128, v122, v122
	v_mul_f32_e32 v129, v123, v123
	v_cvt_pk_bf16_f32 v122, v126, v127
	v_lshlrev_b64 v[126:127], 13, v[142:143]
	v_mul_f32_e32 v152, v124, v124
	v_mul_f32_e32 v153, v125, v125
	v_lshl_add_u64 v[126:127], s[10:11], 0, v[126:127]
	v_ashrrev_i32_e32 v141, 31, v140
	v_cvt_pk_bf16_f32 v123, v128, v129
	v_cvt_pk_bf16_f32 v124, v150, v151
	v_cvt_pk_bf16_f32 v125, v152, v153
	v_lshl_add_u64 v[126:127], v[140:141], 1, v[126:127]
	global_store_dwordx4 v[126:127], v[122:125], off sc1
.LBB0_1245:
	s_or_b64 exec, exec, s[0:1]
	s_nop 0
	v_or_b32_e32 v122, 0x80, v140
	s_movk_i32 s0, 0x1000
	v_cmp_gt_i32_e64 s[8:9], s0, v122
	s_and_saveexec_b64 s[0:1], s[8:9]
	s_cbranch_execz .LBB0_1247
	v_mov_b32_e32 v122, v144
	v_mov_b32_e32 v123, v144
	v_mul_f32_e32 v118, v118, v144
	v_mul_f32_e32 v119, v119, v145
	v_mul_f32_e32 v114, v114, v144
	v_mul_f32_e32 v115, v115, v145
	v_mul_f32_e32 v120, v120, v122
	v_mul_f32_e32 v121, v121, v123
	v_max_f32_e32 v118, 0, v118
	v_max_f32_e32 v114, 0, v114
	v_max_f32_e32 v119, 0, v119
	v_max_f32_e32 v115, 0, v115
	v_mul_f32_e32 v116, v116, v122
	v_mul_f32_e32 v117, v117, v123
	v_mul_f32_e32 v118, v118, v118
	v_mul_f32_e32 v119, v119, v119
	v_mul_f32_e32 v122, v114, v114
	v_mul_f32_e32 v123, v115, v115
	v_max_f32_e32 v114, 0, v120
	v_max_f32_e32 v115, 0, v121
	v_max_f32_e32 v116, 0, v116
	v_max_f32_e32 v117, 0, v117
	v_mul_f32_e32 v120, v114, v114
	v_mul_f32_e32 v121, v115, v115
	v_cvt_pk_bf16_f32 v114, v118, v119
	v_lshlrev_b64 v[118:119], 13, v[142:143]
	v_mul_f32_e32 v124, v116, v116
	v_mul_f32_e32 v125, v117, v117
	v_lshl_add_u64 v[118:119], s[10:11], 0, v[118:119]
	v_ashrrev_i32_e32 v141, 31, v140
	v_cvt_pk_bf16_f32 v115, v120, v121
	v_cvt_pk_bf16_f32 v116, v122, v123
	v_cvt_pk_bf16_f32 v117, v124, v125
	v_lshl_add_u64 v[118:119], v[140:141], 1, v[118:119]
	global_store_dwordx4 v[118:119], v[114:117], off offset:256 sc1
.LBB0_1247:
	s_or_b64 exec, exec, s[0:1]
	s_nop 0
	v_or_b32_e32 v114, 16, v142
	v_ashrrev_i32_e32 v115, 31, v114
	v_lshlrev_b64 v[116:117], 6, v[114:115]
	v_lshl_add_u64 v[128:129], s[2:3], 0, v[116:117]
	v_mov_b32_e32 v116, v243
	v_mov_b32_e32 v117, v116
	s_and_saveexec_b64 s[0:1], vcc
	s_cbranch_execz .LBB0_1249
	v_mov_b32_e32 v118, v116
	v_mov_b32_e32 v119, v116
	v_mul_f32_e32 v110, v110, v116
	v_mul_f32_e32 v111, v111, v117
	v_mul_f32_e32 v106, v106, v116
	v_mul_f32_e32 v107, v107, v117
	v_mul_f32_e32 v112, v112, v118
	v_mul_f32_e32 v113, v113, v119
	v_max_f32_e32 v110, 0, v110
	v_max_f32_e32 v106, 0, v106
	v_max_f32_e32 v111, 0, v111
	v_max_f32_e32 v107, 0, v107
	v_mul_f32_e32 v108, v108, v118
	v_mul_f32_e32 v109, v109, v119
	v_mul_f32_e32 v110, v110, v110
	v_mul_f32_e32 v111, v111, v111
	v_mul_f32_e32 v118, v106, v106
	v_mul_f32_e32 v119, v107, v107
	v_max_f32_e32 v106, 0, v112
	v_max_f32_e32 v107, 0, v113
	v_max_f32_e32 v108, 0, v108
	v_max_f32_e32 v109, 0, v109
	v_mul_f32_e32 v112, v106, v106
	v_mul_f32_e32 v113, v107, v107
	v_cvt_pk_bf16_f32 v106, v110, v111
	v_lshlrev_b64 v[110:111], 13, v[114:115]
	v_mul_f32_e32 v120, v108, v108
	v_mul_f32_e32 v121, v109, v109
	v_lshl_add_u64 v[110:111], s[10:11], 0, v[110:111]
	v_ashrrev_i32_e32 v141, 31, v140
	v_cvt_pk_bf16_f32 v107, v112, v113
	v_cvt_pk_bf16_f32 v108, v118, v119
	v_cvt_pk_bf16_f32 v109, v120, v121
	v_lshl_add_u64 v[110:111], v[140:141], 1, v[110:111]
	global_store_dwordx4 v[110:111], v[106:109], off sc1
.LBB0_1249:
	s_or_b64 exec, exec, s[0:1]
	s_and_saveexec_b64 s[0:1], s[8:9]
	s_cbranch_execz .LBB0_1251
	v_mov_b32_e32 v106, v116
	v_mov_b32_e32 v107, v116
	v_mul_f32_e32 v102, v102, v116
	v_mul_f32_e32 v103, v103, v117
	v_mul_f32_e32 v98, v98, v116
	v_mul_f32_e32 v99, v99, v117
	v_mul_f32_e32 v104, v104, v106
	v_mul_f32_e32 v105, v105, v107
	v_max_f32_e32 v102, 0, v102
	v_max_f32_e32 v98, 0, v98
	v_max_f32_e32 v103, 0, v103
	v_max_f32_e32 v99, 0, v99
	v_mul_f32_e32 v100, v100, v106
	v_mul_f32_e32 v101, v101, v107
	v_mul_f32_e32 v102, v102, v102
	v_mul_f32_e32 v103, v103, v103
	v_mul_f32_e32 v106, v98, v98
	v_mul_f32_e32 v107, v99, v99
	v_max_f32_e32 v98, 0, v104
	v_max_f32_e32 v99, 0, v105
	v_max_f32_e32 v100, 0, v100
	v_max_f32_e32 v101, 0, v101
	v_mul_f32_e32 v104, v98, v98
	v_mul_f32_e32 v105, v99, v99
	v_cvt_pk_bf16_f32 v98, v102, v103
	v_lshlrev_b64 v[102:103], 13, v[114:115]
	v_mul_f32_e32 v108, v100, v100
	v_mul_f32_e32 v109, v101, v101
	v_lshl_add_u64 v[102:103], s[10:11], 0, v[102:103]
	v_ashrrev_i32_e32 v141, 31, v140
	v_cvt_pk_bf16_f32 v99, v104, v105
	v_cvt_pk_bf16_f32 v100, v106, v107
	v_cvt_pk_bf16_f32 v101, v108, v109
	v_lshl_add_u64 v[102:103], v[140:141], 1, v[102:103]
	global_store_dwordx4 v[102:103], v[98:101], off offset:256 sc1
.LBB0_1251:
	s_or_b64 exec, exec, s[0:1]
	s_nop 0
	v_or_b32_e32 v98, 32, v142
	v_ashrrev_i32_e32 v99, 31, v98
	v_lshlrev_b64 v[100:101], 6, v[98:99]
	v_lshl_add_u64 v[112:113], s[2:3], 0, v[100:101]
	v_mov_b32_e32 v100, v244
	v_mov_b32_e32 v101, v100
	s_and_saveexec_b64 s[0:1], vcc
	s_cbranch_execz .LBB0_1253
	v_mov_b32_e32 v102, v100
	v_mov_b32_e32 v103, v100
	v_mul_f32_e32 v94, v94, v100
	v_mul_f32_e32 v95, v95, v101
	v_mul_f32_e32 v90, v90, v100
	v_mul_f32_e32 v91, v91, v101
	v_mul_f32_e32 v96, v96, v102
	v_mul_f32_e32 v97, v97, v103
	v_max_f32_e32 v94, 0, v94
	v_max_f32_e32 v90, 0, v90
	v_max_f32_e32 v95, 0, v95
	v_max_f32_e32 v91, 0, v91
	v_mul_f32_e32 v92, v92, v102
	v_mul_f32_e32 v93, v93, v103
	v_mul_f32_e32 v94, v94, v94
	v_mul_f32_e32 v95, v95, v95
	v_mul_f32_e32 v102, v90, v90
	v_mul_f32_e32 v103, v91, v91
	v_max_f32_e32 v90, 0, v96
	v_max_f32_e32 v91, 0, v97
	v_max_f32_e32 v92, 0, v92
	v_max_f32_e32 v93, 0, v93
	v_mul_f32_e32 v96, v90, v90
	v_mul_f32_e32 v97, v91, v91
	v_cvt_pk_bf16_f32 v90, v94, v95
	v_lshlrev_b64 v[94:95], 13, v[98:99]
	v_mul_f32_e32 v104, v92, v92
	v_mul_f32_e32 v105, v93, v93
	v_lshl_add_u64 v[94:95], s[10:11], 0, v[94:95]
	v_ashrrev_i32_e32 v141, 31, v140
	v_cvt_pk_bf16_f32 v91, v96, v97
	v_cvt_pk_bf16_f32 v92, v102, v103
	v_cvt_pk_bf16_f32 v93, v104, v105
	v_lshl_add_u64 v[94:95], v[140:141], 1, v[94:95]
	global_store_dwordx4 v[94:95], v[90:93], off sc1
.LBB0_1253:
	s_or_b64 exec, exec, s[0:1]
	s_and_saveexec_b64 s[0:1], s[8:9]
	s_cbranch_execz .LBB0_1255
	v_mov_b32_e32 v90, v100
	v_mov_b32_e32 v91, v100
	v_mul_f32_e32 v86, v86, v100
	v_mul_f32_e32 v87, v87, v101
	v_mul_f32_e32 v82, v82, v100
	v_mul_f32_e32 v83, v83, v101
	v_mul_f32_e32 v88, v88, v90
	v_mul_f32_e32 v89, v89, v91
	v_max_f32_e32 v86, 0, v86
	v_max_f32_e32 v82, 0, v82
	v_max_f32_e32 v87, 0, v87
	v_max_f32_e32 v83, 0, v83
	v_mul_f32_e32 v84, v84, v90
	v_mul_f32_e32 v85, v85, v91
	v_mul_f32_e32 v86, v86, v86
	v_mul_f32_e32 v87, v87, v87
	v_mul_f32_e32 v90, v82, v82
	v_mul_f32_e32 v91, v83, v83
	v_max_f32_e32 v82, 0, v88
	v_max_f32_e32 v83, 0, v89
	v_max_f32_e32 v84, 0, v84
	v_max_f32_e32 v85, 0, v85
	v_mul_f32_e32 v88, v82, v82
	v_mul_f32_e32 v89, v83, v83
	v_cvt_pk_bf16_f32 v82, v86, v87
	v_lshlrev_b64 v[86:87], 13, v[98:99]
	v_mul_f32_e32 v92, v84, v84
	v_mul_f32_e32 v93, v85, v85
	v_lshl_add_u64 v[86:87], s[10:11], 0, v[86:87]
	v_ashrrev_i32_e32 v141, 31, v140
	v_cvt_pk_bf16_f32 v83, v88, v89
	v_cvt_pk_bf16_f32 v84, v90, v91
	v_cvt_pk_bf16_f32 v85, v92, v93
	v_lshl_add_u64 v[86:87], v[140:141], 1, v[86:87]
	global_store_dwordx4 v[86:87], v[82:85], off offset:256 sc1
.LBB0_1255:
	s_or_b64 exec, exec, s[0:1]
	s_nop 0
	v_or_b32_e32 v82, 48, v142
	v_ashrrev_i32_e32 v83, 31, v82
	v_lshlrev_b64 v[84:85], 6, v[82:83]
	v_lshl_add_u64 v[96:97], s[2:3], 0, v[84:85]
	v_mov_b32_e32 v84, v245
	v_mov_b32_e32 v85, v84
	s_and_saveexec_b64 s[0:1], vcc
	s_cbranch_execz .LBB0_1257
	v_mov_b32_e32 v86, v84
	v_mov_b32_e32 v87, v84
	v_mul_f32_e32 v78, v78, v84
	v_mul_f32_e32 v79, v79, v85
	v_mul_f32_e32 v74, v74, v84
	v_mul_f32_e32 v75, v75, v85
	v_mul_f32_e32 v80, v80, v86
	v_mul_f32_e32 v81, v81, v87
	v_max_f32_e32 v78, 0, v78
	v_max_f32_e32 v74, 0, v74
	v_max_f32_e32 v79, 0, v79
	v_max_f32_e32 v75, 0, v75
	v_mul_f32_e32 v76, v76, v86
	v_mul_f32_e32 v77, v77, v87
	v_mul_f32_e32 v78, v78, v78
	v_mul_f32_e32 v79, v79, v79
	v_mul_f32_e32 v86, v74, v74
	v_mul_f32_e32 v87, v75, v75
	v_max_f32_e32 v74, 0, v80
	v_max_f32_e32 v75, 0, v81
	v_max_f32_e32 v76, 0, v76
	v_max_f32_e32 v77, 0, v77
	v_mul_f32_e32 v80, v74, v74
	v_mul_f32_e32 v81, v75, v75
	v_cvt_pk_bf16_f32 v74, v78, v79
	v_lshlrev_b64 v[78:79], 13, v[82:83]
	v_mul_f32_e32 v88, v76, v76
	v_mul_f32_e32 v89, v77, v77
	v_lshl_add_u64 v[78:79], s[10:11], 0, v[78:79]
	v_ashrrev_i32_e32 v141, 31, v140
	v_cvt_pk_bf16_f32 v75, v80, v81
	v_cvt_pk_bf16_f32 v76, v86, v87
	v_cvt_pk_bf16_f32 v77, v88, v89
	v_lshl_add_u64 v[78:79], v[140:141], 1, v[78:79]
	global_store_dwordx4 v[78:79], v[74:77], off sc1
.LBB0_1257:
	s_or_b64 exec, exec, s[0:1]
	s_and_saveexec_b64 s[0:1], s[8:9]
	s_cbranch_execz .LBB0_1259
	v_mov_b32_e32 v74, v84
	v_mov_b32_e32 v75, v84
	v_mul_f32_e32 v70, v70, v84
	v_mul_f32_e32 v71, v71, v85
	v_mul_f32_e32 v66, v66, v84
	v_mul_f32_e32 v67, v67, v85
	v_mul_f32_e32 v72, v72, v74
	v_mul_f32_e32 v73, v73, v75
	v_max_f32_e32 v70, 0, v70
	v_max_f32_e32 v66, 0, v66
	v_max_f32_e32 v71, 0, v71
	v_max_f32_e32 v67, 0, v67
	v_mul_f32_e32 v68, v68, v74
	v_mul_f32_e32 v69, v69, v75
	v_mul_f32_e32 v70, v70, v70
	v_mul_f32_e32 v71, v71, v71
	v_mul_f32_e32 v74, v66, v66
	v_mul_f32_e32 v75, v67, v67
	v_max_f32_e32 v66, 0, v72
	v_max_f32_e32 v67, 0, v73
	v_max_f32_e32 v68, 0, v68
	v_max_f32_e32 v69, 0, v69
	v_mul_f32_e32 v72, v66, v66
	v_mul_f32_e32 v73, v67, v67
	v_cvt_pk_bf16_f32 v66, v70, v71
	v_lshlrev_b64 v[70:71], 13, v[82:83]
	v_mul_f32_e32 v76, v68, v68
	v_mul_f32_e32 v77, v69, v69
	v_lshl_add_u64 v[70:71], s[10:11], 0, v[70:71]
	v_ashrrev_i32_e32 v141, 31, v140
	v_cvt_pk_bf16_f32 v67, v72, v73
	v_cvt_pk_bf16_f32 v68, v74, v75
	v_cvt_pk_bf16_f32 v69, v76, v77
	v_lshl_add_u64 v[70:71], v[140:141], 1, v[70:71]
	global_store_dwordx4 v[70:71], v[66:69], off offset:256 sc1
.LBB0_1259:
	s_or_b64 exec, exec, s[0:1]
	s_nop 0
	v_add_u32_e32 v66, 0x80, v142
	v_ashrrev_i32_e32 v67, 31, v66
	v_lshlrev_b64 v[68:69], 6, v[66:67]
	v_lshl_add_u64 v[80:81], s[2:3], 0, v[68:69]
	v_mov_b32_e32 v68, v246
	v_mov_b32_e32 v69, v68
	s_and_saveexec_b64 s[0:1], vcc
	s_cbranch_execz .LBB0_1261
	v_mov_b32_e32 v70, v68
	v_mov_b32_e32 v71, v68
	v_mul_f32_e32 v62, v62, v68
	v_mul_f32_e32 v63, v63, v69
	v_mul_f32_e32 v58, v58, v68
	v_mul_f32_e32 v59, v59, v69
	v_mul_f32_e32 v64, v64, v70
	v_mul_f32_e32 v65, v65, v71
	v_max_f32_e32 v62, 0, v62
	v_max_f32_e32 v58, 0, v58
	v_max_f32_e32 v63, 0, v63
	v_max_f32_e32 v59, 0, v59
	v_mul_f32_e32 v60, v60, v70
	v_mul_f32_e32 v61, v61, v71
	v_mul_f32_e32 v62, v62, v62
	v_mul_f32_e32 v63, v63, v63
	v_mul_f32_e32 v70, v58, v58
	v_mul_f32_e32 v71, v59, v59
	v_max_f32_e32 v58, 0, v64
	v_max_f32_e32 v59, 0, v65
	v_max_f32_e32 v60, 0, v60
	v_max_f32_e32 v61, 0, v61
	v_mul_f32_e32 v64, v58, v58
	v_mul_f32_e32 v65, v59, v59
	v_cvt_pk_bf16_f32 v58, v62, v63
	v_lshlrev_b64 v[62:63], 13, v[66:67]
	v_mul_f32_e32 v72, v60, v60
	v_mul_f32_e32 v73, v61, v61
	v_lshl_add_u64 v[62:63], s[10:11], 0, v[62:63]
	v_ashrrev_i32_e32 v141, 31, v140
	v_cvt_pk_bf16_f32 v59, v64, v65
	v_cvt_pk_bf16_f32 v60, v70, v71
	v_cvt_pk_bf16_f32 v61, v72, v73
	v_lshl_add_u64 v[62:63], v[140:141], 1, v[62:63]
	global_store_dwordx4 v[62:63], v[58:61], off sc1
.LBB0_1261:
	s_or_b64 exec, exec, s[0:1]
	s_and_saveexec_b64 s[0:1], s[8:9]
	s_cbranch_execz .LBB0_1263
	v_mov_b32_e32 v58, v68
	v_mov_b32_e32 v59, v68
	v_mul_f32_e32 v54, v54, v68
	v_mul_f32_e32 v55, v55, v69
	v_mul_f32_e32 v50, v50, v68
	v_mul_f32_e32 v51, v51, v69
	v_mul_f32_e32 v56, v56, v58
	v_mul_f32_e32 v57, v57, v59
	v_max_f32_e32 v54, 0, v54
	v_max_f32_e32 v50, 0, v50
	v_max_f32_e32 v55, 0, v55
	v_max_f32_e32 v51, 0, v51
	v_mul_f32_e32 v52, v52, v58
	v_mul_f32_e32 v53, v53, v59
	v_mul_f32_e32 v54, v54, v54
	v_mul_f32_e32 v55, v55, v55
	v_mul_f32_e32 v58, v50, v50
	v_mul_f32_e32 v59, v51, v51
	v_max_f32_e32 v50, 0, v56
	v_max_f32_e32 v51, 0, v57
	v_max_f32_e32 v52, 0, v52
	v_max_f32_e32 v53, 0, v53
	v_mul_f32_e32 v56, v50, v50
	v_mul_f32_e32 v57, v51, v51
	v_cvt_pk_bf16_f32 v50, v54, v55
	v_lshlrev_b64 v[54:55], 13, v[66:67]
	v_mul_f32_e32 v60, v52, v52
	v_mul_f32_e32 v61, v53, v53
	v_lshl_add_u64 v[54:55], s[10:11], 0, v[54:55]
	v_ashrrev_i32_e32 v141, 31, v140
	v_cvt_pk_bf16_f32 v51, v56, v57
	v_cvt_pk_bf16_f32 v52, v58, v59
	v_cvt_pk_bf16_f32 v53, v60, v61
	v_lshl_add_u64 v[54:55], v[140:141], 1, v[54:55]
	global_store_dwordx4 v[54:55], v[50:53], off offset:256 sc1
.LBB0_1263:
	s_or_b64 exec, exec, s[0:1]
	s_nop 0
	v_add_u32_e32 v50, 0x90, v142
	v_ashrrev_i32_e32 v51, 31, v50
	v_lshlrev_b64 v[52:53], 6, v[50:51]
	v_lshl_add_u64 v[64:65], s[2:3], 0, v[52:53]
	v_mov_b32_e32 v52, v247
	v_mov_b32_e32 v53, v52
	s_and_saveexec_b64 s[0:1], vcc
	s_cbranch_execz .LBB0_1265
	v_mov_b32_e32 v54, v52
	v_mov_b32_e32 v55, v52
	v_mul_f32_e32 v46, v46, v52
	v_mul_f32_e32 v47, v47, v53
	v_mul_f32_e32 v42, v42, v52
	v_mul_f32_e32 v43, v43, v53
	v_mul_f32_e32 v48, v48, v54
	v_mul_f32_e32 v49, v49, v55
	v_max_f32_e32 v46, 0, v46
	v_max_f32_e32 v42, 0, v42
	v_max_f32_e32 v47, 0, v47
	v_max_f32_e32 v43, 0, v43
	v_mul_f32_e32 v44, v44, v54
	v_mul_f32_e32 v45, v45, v55
	v_mul_f32_e32 v46, v46, v46
	v_mul_f32_e32 v47, v47, v47
	v_mul_f32_e32 v54, v42, v42
	v_mul_f32_e32 v55, v43, v43
	v_max_f32_e32 v42, 0, v48
	v_max_f32_e32 v43, 0, v49
	v_max_f32_e32 v44, 0, v44
	v_max_f32_e32 v45, 0, v45
	v_mul_f32_e32 v48, v42, v42
	v_mul_f32_e32 v49, v43, v43
	v_cvt_pk_bf16_f32 v42, v46, v47
	v_lshlrev_b64 v[46:47], 13, v[50:51]
	v_mul_f32_e32 v56, v44, v44
	v_mul_f32_e32 v57, v45, v45
	v_lshl_add_u64 v[46:47], s[10:11], 0, v[46:47]
	v_ashrrev_i32_e32 v141, 31, v140
	v_cvt_pk_bf16_f32 v43, v48, v49
	v_cvt_pk_bf16_f32 v44, v54, v55
	v_cvt_pk_bf16_f32 v45, v56, v57
	v_lshl_add_u64 v[46:47], v[140:141], 1, v[46:47]
	global_store_dwordx4 v[46:47], v[42:45], off sc1
.LBB0_1265:
	s_or_b64 exec, exec, s[0:1]
	s_and_saveexec_b64 s[0:1], s[8:9]
	s_cbranch_execz .LBB0_1267
	v_mov_b32_e32 v42, v52
	v_mov_b32_e32 v43, v52
	v_mul_f32_e32 v38, v38, v52
	v_mul_f32_e32 v39, v39, v53
	v_mul_f32_e32 v34, v34, v52
	v_mul_f32_e32 v35, v35, v53
	v_mul_f32_e32 v40, v40, v42
	v_mul_f32_e32 v41, v41, v43
	v_max_f32_e32 v38, 0, v38
	v_max_f32_e32 v34, 0, v34
	v_max_f32_e32 v39, 0, v39
	v_max_f32_e32 v35, 0, v35
	v_mul_f32_e32 v36, v36, v42
	v_mul_f32_e32 v37, v37, v43
	v_mul_f32_e32 v38, v38, v38
	v_mul_f32_e32 v39, v39, v39
	v_mul_f32_e32 v42, v34, v34
	v_mul_f32_e32 v43, v35, v35
	v_max_f32_e32 v34, 0, v40
	v_max_f32_e32 v35, 0, v41
	v_max_f32_e32 v36, 0, v36
	v_max_f32_e32 v37, 0, v37
	v_mul_f32_e32 v40, v34, v34
	v_mul_f32_e32 v41, v35, v35
	v_cvt_pk_bf16_f32 v34, v38, v39
	v_lshlrev_b64 v[38:39], 13, v[50:51]
	v_mul_f32_e32 v44, v36, v36
	v_mul_f32_e32 v45, v37, v37
	v_lshl_add_u64 v[38:39], s[10:11], 0, v[38:39]
	v_ashrrev_i32_e32 v141, 31, v140
	v_cvt_pk_bf16_f32 v35, v40, v41
	v_cvt_pk_bf16_f32 v36, v42, v43
	v_cvt_pk_bf16_f32 v37, v44, v45
	v_lshl_add_u64 v[38:39], v[140:141], 1, v[38:39]
	global_store_dwordx4 v[38:39], v[34:37], off offset:256 sc1
.LBB0_1267:
	s_or_b64 exec, exec, s[0:1]
	s_nop 0
	v_add_u32_e32 v34, 0xa0, v142
	v_ashrrev_i32_e32 v35, 31, v34
	v_lshlrev_b64 v[36:37], 6, v[34:35]
	v_lshl_add_u64 v[48:49], s[2:3], 0, v[36:37]
	v_mov_b32_e32 v36, v248
	v_mov_b32_e32 v37, v36
	s_and_saveexec_b64 s[0:1], vcc
	s_cbranch_execz .LBB0_1269
	v_mov_b32_e32 v38, v36
	v_mov_b32_e32 v39, v36
	v_mul_f32_e32 v30, v30, v36
	v_mul_f32_e32 v31, v31, v37
	v_mul_f32_e32 v26, v26, v36
	v_mul_f32_e32 v27, v27, v37
	v_mul_f32_e32 v32, v32, v38
	v_mul_f32_e32 v33, v33, v39
	v_max_f32_e32 v30, 0, v30
	v_max_f32_e32 v26, 0, v26
	v_max_f32_e32 v31, 0, v31
	v_max_f32_e32 v27, 0, v27
	v_mul_f32_e32 v28, v28, v38
	v_mul_f32_e32 v29, v29, v39
	v_mul_f32_e32 v30, v30, v30
	v_mul_f32_e32 v31, v31, v31
	v_mul_f32_e32 v38, v26, v26
	v_mul_f32_e32 v39, v27, v27
	v_max_f32_e32 v26, 0, v32
	v_max_f32_e32 v27, 0, v33
	v_max_f32_e32 v28, 0, v28
	v_max_f32_e32 v29, 0, v29
	v_mul_f32_e32 v32, v26, v26
	v_mul_f32_e32 v33, v27, v27
	v_cvt_pk_bf16_f32 v26, v30, v31
	v_lshlrev_b64 v[30:31], 13, v[34:35]
	v_mul_f32_e32 v40, v28, v28
	v_mul_f32_e32 v41, v29, v29
	v_lshl_add_u64 v[30:31], s[10:11], 0, v[30:31]
	v_ashrrev_i32_e32 v141, 31, v140
	v_cvt_pk_bf16_f32 v27, v32, v33
	v_cvt_pk_bf16_f32 v28, v38, v39
	v_cvt_pk_bf16_f32 v29, v40, v41
	v_lshl_add_u64 v[30:31], v[140:141], 1, v[30:31]
	global_store_dwordx4 v[30:31], v[26:29], off sc1
.LBB0_1269:
	s_or_b64 exec, exec, s[0:1]
	s_and_saveexec_b64 s[0:1], s[8:9]
	s_cbranch_execz .LBB0_1271
	v_mov_b32_e32 v26, v36
	v_mov_b32_e32 v27, v36
	v_mul_f32_e32 v22, v22, v36
	v_mul_f32_e32 v23, v23, v37
	v_mul_f32_e32 v18, v18, v36
	v_mul_f32_e32 v19, v19, v37
	v_mul_f32_e32 v24, v24, v26
	v_mul_f32_e32 v25, v25, v27
	v_max_f32_e32 v22, 0, v22
	v_max_f32_e32 v18, 0, v18
	v_max_f32_e32 v23, 0, v23
	v_max_f32_e32 v19, 0, v19
	v_mul_f32_e32 v20, v20, v26
	v_mul_f32_e32 v21, v21, v27
	v_mul_f32_e32 v22, v22, v22
	v_mul_f32_e32 v23, v23, v23
	v_mul_f32_e32 v26, v18, v18
	v_mul_f32_e32 v27, v19, v19
	v_max_f32_e32 v18, 0, v24
	v_max_f32_e32 v19, 0, v25
	v_max_f32_e32 v20, 0, v20
	v_max_f32_e32 v21, 0, v21
	v_mul_f32_e32 v24, v18, v18
	v_mul_f32_e32 v25, v19, v19
	v_cvt_pk_bf16_f32 v18, v22, v23
	v_lshlrev_b64 v[22:23], 13, v[34:35]
	v_mul_f32_e32 v28, v20, v20
	v_mul_f32_e32 v29, v21, v21
	v_lshl_add_u64 v[22:23], s[10:11], 0, v[22:23]
	v_ashrrev_i32_e32 v141, 31, v140
	v_cvt_pk_bf16_f32 v19, v24, v25
	v_cvt_pk_bf16_f32 v20, v26, v27
	v_cvt_pk_bf16_f32 v21, v28, v29
	v_lshl_add_u64 v[22:23], v[140:141], 1, v[22:23]
	global_store_dwordx4 v[22:23], v[18:21], off offset:256 sc1
.LBB0_1271:
	s_or_b64 exec, exec, s[0:1]
	s_nop 0
	v_add_u32_e32 v18, 0xb0, v142
	v_ashrrev_i32_e32 v19, 31, v18
	v_lshlrev_b64 v[20:21], 6, v[18:19]
	v_lshl_add_u64 v[32:33], s[2:3], 0, v[20:21]
	v_mov_b32_e32 v20, v249
	v_mov_b32_e32 v21, v20
	s_and_saveexec_b64 s[0:1], vcc
	s_cbranch_execz .LBB0_1273
	v_mov_b32_e32 v22, v20
	v_mov_b32_e32 v23, v20
	v_mul_f32_e32 v14, v14, v20
	v_mul_f32_e32 v15, v15, v21
	v_mul_f32_e32 v10, v10, v20
	v_mul_f32_e32 v11, v11, v21
	v_mul_f32_e32 v16, v16, v22
	v_mul_f32_e32 v17, v17, v23
	v_max_f32_e32 v14, 0, v14
	v_max_f32_e32 v10, 0, v10
	v_max_f32_e32 v15, 0, v15
	v_max_f32_e32 v11, 0, v11
	v_mul_f32_e32 v12, v12, v22
	v_mul_f32_e32 v13, v13, v23
	v_mul_f32_e32 v14, v14, v14
	v_mul_f32_e32 v15, v15, v15
	v_mul_f32_e32 v22, v10, v10
	v_mul_f32_e32 v23, v11, v11
	v_max_f32_e32 v10, 0, v16
	v_max_f32_e32 v11, 0, v17
	v_max_f32_e32 v12, 0, v12
	v_max_f32_e32 v13, 0, v13
	v_mul_f32_e32 v16, v10, v10
	v_mul_f32_e32 v17, v11, v11
	v_cvt_pk_bf16_f32 v10, v14, v15
	v_lshlrev_b64 v[14:15], 13, v[18:19]
	v_mul_f32_e32 v24, v12, v12
	v_mul_f32_e32 v25, v13, v13
	v_lshl_add_u64 v[14:15], s[10:11], 0, v[14:15]
	v_ashrrev_i32_e32 v141, 31, v140
	v_cvt_pk_bf16_f32 v11, v16, v17
	v_cvt_pk_bf16_f32 v12, v22, v23
	v_cvt_pk_bf16_f32 v13, v24, v25
	v_lshl_add_u64 v[14:15], v[140:141], 1, v[14:15]
	global_store_dwordx4 v[14:15], v[10:13], off sc1
.LBB0_1273:
	s_or_b64 exec, exec, s[0:1]
	s_and_saveexec_b64 s[0:1], s[8:9]
	s_cbranch_execz .LBB0_1275
	v_mov_b32_e32 v10, v20
	v_mov_b32_e32 v11, v20
	v_mul_f32_e32 v6, v6, v20
	v_mul_f32_e32 v7, v7, v21
	v_mul_f32_e32 v2, v2, v20
	v_mul_f32_e32 v3, v3, v21
	v_mul_f32_e32 v8, v8, v10
	v_mul_f32_e32 v9, v9, v11
	v_max_f32_e32 v6, 0, v6
	v_max_f32_e32 v2, 0, v2
	v_max_f32_e32 v7, 0, v7
	v_max_f32_e32 v3, 0, v3
	v_mul_f32_e32 v4, v4, v10
	v_mul_f32_e32 v5, v5, v11
	v_mul_f32_e32 v6, v6, v6
	v_mul_f32_e32 v7, v7, v7
	v_mul_f32_e32 v10, v2, v2
	v_mul_f32_e32 v11, v3, v3
	v_max_f32_e32 v2, 0, v8
	v_max_f32_e32 v3, 0, v9
	v_max_f32_e32 v4, 0, v4
	v_max_f32_e32 v5, 0, v5
	v_mul_f32_e32 v8, v2, v2
	v_mul_f32_e32 v9, v3, v3
	v_cvt_pk_bf16_f32 v2, v6, v7
	v_lshlrev_b64 v[6:7], 13, v[18:19]
	v_mul_f32_e32 v12, v4, v4
	v_mul_f32_e32 v13, v5, v5
	v_lshl_add_u64 v[6:7], s[10:11], 0, v[6:7]
	v_ashrrev_i32_e32 v141, 31, v140
	v_cvt_pk_bf16_f32 v3, v8, v9
	v_cvt_pk_bf16_f32 v4, v10, v11
	v_cvt_pk_bf16_f32 v5, v12, v13
	v_lshl_add_u64 v[6:7], v[140:141], 1, v[6:7]
	global_store_dwordx4 v[6:7], v[2:5], off offset:256 sc1
